# phase 10 GEMM tile order: row-group size 2 -> 4 (an XCD's 32 workgroups per round cover 4 row panels x 8 column panels instead of 2 x 16) for more L2 operand reuse
# baseline (speedup 1.0000x reference)
.LBB0_1236:
	s_cmp_lt_i32 s92, 11
	s_cselect_b64 s[0:1], -1, 0
	s_and_b64 s[4:5], s[0:1], s[4:5]
	s_andn2_b64 vcc, exec, s[4:5]
	s_cbranch_vccnz .LBB0_1249
	s_cmpk_gt_i32 s20, 0xaff
	v_readfirstlane_b32 s38, v160
	s_cbranch_scc1 .LBB0_1249
	v_lshrrev_b32_e32 v0, 5, v160
	v_lshrrev_b32_e32 v2, 1, v160
	v_and_b32_e32 v0, 4, v0
	v_bfe_u32 v1, v160, 2, 2
	v_and_b32_e32 v11, 24, v2
	v_or3_b32 v0, v0, v1, v11
	v_lshlrev_b32_e32 v1, 4, v160
	v_add_u32_e32 v8, 0x2000, v1
	v_lshrrev_b32_e32 v2, 7, v8
	s_movk_i32 s4, 0xe0
	v_and_b32_e32 v4, 32, v160
	s_add_u32 s39, s22, 0x30bc000
	v_and_or_b32 v3, v2, s4, v0
	v_bitop3_b32 v9, v1, v4, 48 bitop3:0x6c
	v_and_b32_e32 v10, 64, v160
	v_bfe_u32 v12, v160, 2, 4
	s_movk_i32 s4, 0xf0
	s_addc_u32 s40, s23, 0
	v_or_b32_e32 v1, v9, v10
	v_and_or_b32 v2, v2, s4, v12
	s_add_u32 s41, s22, 0x900000
	v_lshl_or_b32 v130, v2, 11, v1
	v_lshrrev_b32_e32 v2, 3, v160
	s_movk_i32 s4, 0x60
	s_addc_u32 s42, s23, 0
	v_and_or_b32 v0, v2, s4, v0
	s_movk_i32 s4, 0x70
	s_ashr_i32 s44, s20, 31
	v_lshl_or_b32 v132, v0, 11, v1
	v_and_or_b32 v0, v2, s4, v12
	s_lshr_b32 s4, s44, 29
	s_add_i32 s4, s20, s4
	s_lshr_b32 s8, s38, 6
	s_ashr_i32 s6, s4, 3
	s_and_b32 s4, s4, -8
	s_lshr_b32 s5, s38, 8
	s_lshl_b32 s43, s8, 10
	s_sub_i32 s4, s20, s4
	s_cmp_lt_i32 s4, 0
	s_movk_i32 s45, 0x161
	s_cselect_b32 s7, s45, 0x160
	s_mul_i32 s4, s4, s7
	s_add_i32 s4, s4, s6
	s_mul_hi_i32 s6, s4, 0x2e8ba2e9
	s_lshr_b32 s7, s6, 31
	s_ashr_i32 s6, s6, 4
	s_add_i32 s6, s6, s7
	s_lshl_b32 s7, s6, 2
	s_mulk_i32 s6, 0x58
	s_sub_i32 s6, s4, s6
	s_and_b32 s9, s6, 3
	s_lshr_b32 s4, s6, 2
	s_nop 0
	s_nop 0
	s_nop 0
	s_nop 0
	s_nop 0
	s_nop 0
	s_add_i32 s24, s7, s9
	s_ashr_i32 s25, s24, 31
	s_bfe_i64 s[10:11], s[4:5], 0x100000
	s_lshl_b64 s[6:7], s[24:25], 19
	s_lshl_b64 s[10:11], s[10:11], 19
	s_add_u32 s28, s41, s10
	s_addc_u32 s29, s42, s11
	s_add_i32 s25, s43, 0
	s_add_i32 m0, s25, 0x10000
	v_lshl_or_b32 v128, v3, 11, v1
	global_load_lds_dwordx4 v132, s[28:29]
	s_add_i32 m0, s25, 0x12000
	s_add_u32 s26, s39, s6
	v_lshl_or_b32 v134, v0, 11, v1
	global_load_lds_dwordx4 v128, s[28:29]
	s_addc_u32 s27, s40, s7
	s_mov_b32 m0, s25
	s_add_i32 s46, s25, 0x2000
	global_load_lds_dwordx4 v134, s[26:27]
	s_mov_b32 m0, s46
	s_add_u32 s6, s28, 0x40000
	global_load_lds_dwordx4 v130, s[26:27]
	s_addc_u32 s7, s29, 0
	s_add_i32 m0, s25, 0x14000
	v_mov_b32_e32 v133, 0
	global_load_lds_dwordx4 v132, s[6:7]
	s_add_i32 m0, s25, 0x16000
	v_mov_b32_e32 v129, v133
	global_load_lds_dwordx4 v128, s[6:7]
	s_add_u32 s6, s26, 0x40000
	s_addc_u32 s7, s27, 0
	s_add_i32 s47, s25, 0x4000
	s_mov_b32 m0, s47
	s_add_i32 s48, s25, 0x6000
	global_load_lds_dwordx4 v134, s[6:7]
	s_mov_b32 m0, s48
	v_mov_b32_e32 v135, v133
	global_load_lds_dwordx4 v130, s[6:7]
	v_mov_b32_e32 v131, v133
	s_mov_b32 s49, 0
	v_lshl_add_u64 v[6:7], s[28:29], 0, v[132:133]
	v_lshl_add_u64 v[4:5], s[28:29], 0, v[128:129]
	v_lshl_add_u64 v[2:3], s[26:27], 0, v[134:135]
	s_cmp_lg_u32 s5, 1
	v_lshl_add_u64 v[0:1], s[26:27], 0, v[130:131]
	s_cbranch_scc1 .LBB0_1240
	s_barrier

.LBB0_1241:
	s_add_i32 s49, s49, 1
	s_mul_i32 s4, s49, s52
	s_mul_hi_u32 s5, s49, s53
	s_add_i32 s5, s5, s4
	s_mul_i32 s4, s49, s53
	s_add_u32 s14, s4, s20
	s_addc_u32 s15, s5, s44
	v_cmp_gt_i64_e64 s[4:5], s[14:15], v[142:143]
	s_and_b64 vcc, exec, s[4:5]
	s_cbranch_vccnz .LBB0_1243
	s_ashr_i32 s10, s14, 31
	s_lshr_b32 s10, s10, 29
	s_add_i32 s10, s14, s10
	s_ashr_i32 s11, s10, 3
	s_and_b32 s10, s10, -8
	s_sub_i32 s10, s14, s10
	s_cmp_lt_i32 s10, 0
	s_cselect_b32 s12, s45, 0x160
	s_mul_i32 s10, s10, s12
	s_add_i32 s10, s10, s11
	s_mul_hi_i32 s11, s10, 0x2e8ba2e9
	s_lshr_b32 s12, s11, 31
	s_ashr_i32 s11, s11, 4
	s_add_i32 s11, s11, s12
	s_lshl_b32 s12, s11, 2
	s_sub_i32 s13, 0x80, s12
	s_min_i32 s13, s13, 4
	s_abs_i32 s16, s13
	v_cvt_f32_u32_e32 v0, s16
	s_sub_i32 s30, 0, s16
	s_mulk_i32 s11, 0x58
	s_sub_i32 s11, s10, s11
	v_rcp_iflag_f32_e32 v0, v0
	s_abs_i32 s10, s11
	s_xor_b32 s17, s11, s13
	s_ashr_i32 s17, s17, 31
	v_mul_f32_e32 v0, 0x4f7ffffe, v0
	v_cvt_u32_f32_e32 v0, v0
	s_nop 0
	v_readfirstlane_b32 s31, v0
	s_mul_i32 s30, s30, s31
	s_mul_hi_u32 s30, s31, s30
	s_add_i32 s31, s31, s30
	s_mul_hi_u32 s30, s10, s31
	s_mul_i32 s31, s30, s16
	s_sub_i32 s10, s10, s31
	s_add_i32 s58, s30, 1
	s_sub_i32 s31, s10, s16
	s_cmp_ge_u32 s10, s16
	s_cselect_b32 s30, s58, s30
	s_cselect_b32 s10, s31, s10
	s_add_i32 s31, s30, 1
	s_cmp_ge_u32 s10, s16
	s_cselect_b32 s10, s31, s30
	s_xor_b32 s10, s10, s17
	s_sub_i32 s10, s10, s17
	s_mul_i32 s13, s10, s13
	s_sub_i32 s11, s11, s13
	s_add_i32 s12, s12, s11
